# phase 0: every other group of eight workgroups walks its prep units last to first (filter MLP before weight conversion)
# speedup vs baseline: 1.0178x; 1.0047x over previous
.LBB0_5:
	s_or_b64 exec, exec, s[6:7]
	s_load_dwordx16 s[8:23], s[0:1], 0x40
	s_load_dwordx16 s[80:95], s[0:1], 0x80
	s_cmp_lt_i32 s68, 1
	s_cselect_b64 s[6:7], -1, 0
	s_cmp_gt_i32 s69, 0
	s_waitcnt lgkmcnt(0)
	v_writelane_b32 v240, s8, 6
	s_nop 1
	v_writelane_b32 v240, s9, 7
	v_writelane_b32 v240, s10, 8
	v_writelane_b32 v240, s11, 9
	v_writelane_b32 v240, s12, 10
	v_writelane_b32 v240, s13, 11
	v_writelane_b32 v240, s14, 12
	v_writelane_b32 v240, s15, 13
	v_writelane_b32 v240, s16, 14
	v_writelane_b32 v240, s17, 15
	v_writelane_b32 v240, s18, 16
	v_writelane_b32 v240, s19, 17
	v_writelane_b32 v240, s20, 18
	v_writelane_b32 v240, s21, 19
	v_writelane_b32 v240, s22, 20
	v_writelane_b32 v240, s23, 21
	s_cselect_b64 s[8:9], -1, 0
	s_and_b64 s[52:53], s[6:7], s[8:9]
	s_andn2_b64 vcc, exec, s[52:53]
	s_cbranch_vccnz .LBB0_68
	s_cmpk_gt_i32 s2, 0x510
	s_cbranch_scc1 .LBB0_68
	v_add_u32_e32 v3, -1, v1
	v_and_b32_e32 v2, 63, v1
	v_and_b32_e32 v3, 15, v3
	v_lshlrev_b32_e32 v54, 2, v2
	v_cvt_f32_ubyte0_e32 v3, v3
	v_mov_b32_e32 v102, 0x38d1b717
	v_add_u32_e32 v101, 0, v54
	v_fmac_f32_e32 v102, 0x3f7fff90, v3
	v_and_b32_e32 v3, 0x3c0, v1
	v_and_b32_e32 v107, 31, v1
	v_and_b32_e32 v5, 0x3e0, v1
	v_lshl_add_u32 v106, v3, 2, v101
	v_lshrrev_b32_e32 v3, 5, v1
	v_lshlrev_b32_e32 v5, 2, v5
	v_lshlrev_b32_e32 v6, 2, v107
	s_add_u32 s54, s66, 0x1400000
	v_lshl_add_u32 v108, v3, 8, 0
	v_add3_u32 v109, 0, v5, v6
	v_mul_u32_u24_e32 v5, 0x700, v3
	s_addc_u32 s55, s67, 0
	v_add3_u32 v110, v108, v5, v6
	v_mul_u32_u24_e32 v5, 0x1800, v3
	s_add_u32 s28, s66, 0x1600000
	v_or_b32_e32 v111, v5, v107
	v_lshlrev_b32_e32 v5, 4, v1
	s_addc_u32 s29, s67, 0
	s_load_dwordx16 s[12:27], s[0:1], 0x0
	v_and_b32_e32 v8, 0x3f0, v5
	v_lshlrev_b32_e32 v5, 5, v1
	s_add_u32 s96, s66, 0x1800000
	v_lshrrev_b32_e32 v113, 1, v1
	v_and_b32_e32 v56, 32, v5
	s_addc_u32 s97, s67, 0
	v_mov_b32_e32 v55, 0
	v_lshlrev_b32_e32 v5, 2, v113
	v_mul_u32_u24_e32 v7, 0x404, v56
	s_add_u32 s72, s66, 0x1a00000
	v_lshlrev_b32_e32 v4, 2, v1
	v_add3_u32 v114, 0, v5, v7
	s_addc_u32 s73, s67, 0
	v_mov_b32_e32 v9, v55
	v_mov_b32_e32 v5, v55
	v_writelane_b32 v240, s3, 22
	v_add_u32_e32 v112, 0, v8
	s_add_u32 s33, s66, 0x1a80000
	v_lshl_add_u64 v[66:67], s[94:95], 0, v[8:9]
	v_lshl_add_u64 v[68:69], s[92:93], 0, v[8:9]
	v_lshl_add_u64 v[70:71], s[90:91], 0, v[8:9]
	s_waitcnt lgkmcnt(0)
	v_lshl_add_u64 v[72:73], s[26:27], 0, v[8:9]
	v_lshl_add_u64 v[8:9], s[66:67], 0, v[4:5]
	s_mov_b64 s[8:9], 0x1a20000
	v_lshrrev_b32_e32 v57, 6, v1
	s_movk_i32 s6, 0xa0
	v_mul_u32_u24_e32 v3, 0x60000, v3
	s_addc_u32 s3, s67, 0
	v_readlane_b32 s36, v240, 6
	v_mov_b32_e32 v7, v55
	v_lshl_add_u64 v[82:83], v[8:9], 0, s[8:9]
	s_movk_i32 s8, 0xf000
	v_mad_u32_u24 v104, v57, s6, 0
	s_movk_i32 s6, 0x60
	s_add_u32 s57, s66, 0x1a40000
	v_readlane_b32 s37, v240, 7
	v_readlane_b32 s44, v240, 14
	v_readlane_b32 s45, v240, 15
	v_readlane_b32 s46, v240, 16
	v_readlane_b32 s47, v240, 17
	v_readlane_b32 s48, v240, 18
	v_readlane_b32 s49, v240, 19
	v_readlane_b32 s50, v240, 20
	v_readlane_b32 s51, v240, 21
	v_lshl_add_u64 v[6:7], s[22:23], 0, v[6:7]
	v_lshlrev_b32_e32 v10, 2, v3
	v_mov_b32_e32 v11, v55
	v_lshl_add_u32 v3, v57, 8, 0
	v_lshl_add_u64 v[8:9], s[18:19], 0, v[4:5]
	s_mov_b32 s9, -1
	s_mov_b32 s18, 0x54442d18
	v_or_b32_e32 v100, 0xffffc000, v57
	v_mul_u32_u24_e32 v103, 0xa0, v57
	v_add_u32_e32 v105, 0, v4
	v_cmp_gt_u32_e64 s[6:7], s6, v1
	s_addc_u32 s74, s67, 0
	v_lshl_add_u64 v[58:59], s[46:47], 0, v[54:55]
	v_lshl_add_u64 v[60:61], s[84:85], 0, v[54:55]
	v_lshl_add_u64 v[62:63], s[50:51], 0, v[54:55]
	v_lshl_add_u64 v[64:65], s[82:83], 0, v[54:55]
	v_lshl_add_u64 v[74:75], s[44:45], 0, v[54:55]
	s_movk_i32 s56, 0x1000
	v_add_u32_e32 v115, 0x1000, v3
	v_lshl_add_u64 v[76:77], s[48:49], 0, v[54:55]
	v_add_u32_e32 v116, 0x2000, v3
	v_lshl_add_u64 v[78:79], s[80:81], 0, v[54:55]
	v_lshl_add_u64 v[80:81], s[36:37], 0, v[4:5]
	v_lshl_add_u64 v[84:85], v[8:9], 0, s[8:9]
	v_lshl_add_u64 v[86:87], s[20:21], 0, v[4:5]
	s_mov_b32 s19, 0x401921fb
	v_lshlrev_b32_e32 v88, 1, v2
	v_mul_u32_u24_e32 v117, 0x404, v57
	v_add_u32_e32 v118, 0xfffffe00, v1
	v_mov_b32_e32 v119, 0x1000
	v_mov_b32_e32 v120, 0x100
	v_mov_b32_e32 v121, 0xffffff08
	v_mov_b32_e32 v122, 0x80000
	v_mov_b32_e32 v123, 0x8000
	v_mov_b32_e32 v124, 0x7f800000
	v_lshl_add_u64 v[90:91], v[6:7], 0, v[10:11]
	s_mov_b32 s21, 0x10e000
	s_mov_b32 s20, 0x114000
	s_mov_b32 s22, 0x11a000
	s_mov_b32 s58, 0x120000
	s_mov_b32 s59, 0x126000
	s_mov_b32 s60, 0x12c000
	s_mov_b32 s61, 0x132000
	s_mov_b32 s62, 0x138000
	s_mov_b32 s63, 0x13e000
	s_mov_b32 s75, 0x144000
	s_mov_b32 s76, 0x14a000
	s_mov_b32 s77, 0x150000
	s_mov_b32 s78, 0x156000
	s_mov_b32 s79, 0x15c000
	s_mov_b32 s80, 0x162000
	s_mov_b32 s81, 0x168000
	s_mov_b32 s82, 0x16e000
	s_mov_b32 s83, 0x174000
	s_mov_b32 s84, 0x17a000
	s_mov_b32 s85, 0xa000
	s_mov_b32 s90, s2
	s_mov_b32 s32, s70
	s_cmpk_lg_u32 s70, 0x100
	s_cbranch_scc1 .Lp0_order
	s_bitcmp1_b32 s2, 3
	s_cbranch_scc0 .Lp0_order
	s_movk_i32 s32, 0xff00
	s_addk_i32 s90, 0x400
	s_cmpk_gt_u32 s2, 16
	s_cbranch_scc1 .Lp0_order
	s_addk_i32 s90, 0x100
.Lp0_order:
	v_cmp_gt_u32_e64 s[8:9], 33, v2
	s_mov_b32 s31, 0
	v_cmp_ne_u32_e64 s[10:11], 0, v2
	v_cmp_lt_u32_e64 s[12:13], 16, v2
	s_mov_b64 s[34:35], 0x800
	v_readlane_b32 s38, v240, 8
	v_readlane_b32 s39, v240, 9
	v_readlane_b32 s40, v240, 10
	v_readlane_b32 s41, v240, 11
	v_readlane_b32 s42, v240, 12
	v_readlane_b32 s43, v240, 13
	s_branch .LBB0_9
.LBB0_8:
	s_add_i32 s90, s90, s32
	s_cmpk_lt_u32 s90, 0x511
	s_cbranch_scc0 .LBB0_67
